# static priority raise (s_setprio 1) for the younger wave half (waves 4-7) during the two diff-attention phases, no other s_setprio in those phases
# speedup vs baseline: 1.0011x; 1.0011x over previous
.LBB0_263:
	s_and_b32 s0, s85, 0x3fffffc0
	s_lshl_b32 s0, s0, 2
	s_add_i32 s0, s0, 0
	s_add_i32 s0, s0, 0x20000
	s_cmp_lt_i32 s62, 3
	v_writelane_b32 v255, s0, 27
	s_cselect_b64 s[0:1], -1, 0
	s_cmp_gt_i32 s63, 2
	s_cselect_b64 s[2:3], -1, 0
	s_and_b64 s[0:1], s[0:1], s[2:3]
	s_andn2_b64 vcc, exec, s[0:1]
	s_cbranch_vccnz .LBB0_356
	v_readfirstlane_b32 s0, v212
	s_cmp_lt_u32 s0, 0x100
	s_cbranch_scc1 .Lmy_prio_a
	s_setprio 1
.Lmy_prio_a:
	v_mov_b32_e32 v0, v212
	v_readlane_b32 s0, v255, 7
	v_and_b32_e32 v0, 63, v0
	v_lshlrev_b32_e32 v0, 2, v0
	v_readlane_b32 s12, v255, 19
	v_readlane_b32 s13, v255, 20
	s_nop 4
	global_load_dword v1, v0, s[12:13] offset:768
	global_load_dword v2, v0, s[12:13] offset:1024
	global_load_dword v3, v0, s[12:13] offset:1792
	global_load_dword v4, v0, s[12:13] offset:1280
	global_load_dword v5, v0, s[12:13] offset:256
	global_load_dword v6, v0, s[12:13] offset:512
	global_load_dword v7, v0, s[12:13]
	s_nop 0
	global_load_dword v0, v0, s[12:13] offset:1536
	v_mbcnt_lo_u32_b32 v8, -1, 0
	v_mbcnt_hi_u32_b32 v8, -1, v8
	v_and_b32_e32 v9, 64, v8
	v_xor_b32_e32 v10, 1, v8
	v_add_u32_e32 v9, 64, v9
	v_cmp_lt_i32_e32 vcc, v10, v9
	v_xor_b32_e32 v11, 2, v8
	v_xor_b32_e32 v12, 4, v8
	v_cndmask_b32_e32 v10, v8, v10, vcc
	v_lshlrev_b32_e32 v213, 2, v10
	v_cmp_lt_i32_e32 vcc, v11, v9
	v_xor_b32_e32 v13, 8, v8
	v_xor_b32_e32 v14, 16, v8
	v_xor_b32_e32 v15, 32, v8
	v_readlane_b32 s5, v255, 12
	s_cmpk_gt_i32 s84, 0x3ff
	s_mov_b32 s5, 0
	v_readlane_b32 s1, v255, 8
	v_readlane_b32 s2, v255, 9
	v_readlane_b32 s3, v255, 10
	v_readlane_b32 s4, v255, 11
	v_readlane_b32 s6, v255, 13
	v_readlane_b32 s7, v255, 14
	v_readlane_b32 s8, v255, 15
	v_readlane_b32 s9, v255, 16
	v_readlane_b32 s10, v255, 17
	v_readlane_b32 s11, v255, 18
	v_readlane_b32 s14, v255, 21
	v_readlane_b32 s15, v255, 22
	s_waitcnt vmcnt(0)
	v_mul_f32_e32 v3, v4, v3
	v_mul_f32_e32 v1, v5, v1
	v_cndmask_b32_e32 v4, v8, v11, vcc
	v_fmac_f32_e32 v1, v7, v6
	v_fmac_f32_e32 v3, v2, v0
	ds_bpermute_b32 v0, v213, v1
	ds_bpermute_b32 v2, v213, v3
	v_lshlrev_b32_e32 v214, 2, v4
	v_cmp_lt_i32_e32 vcc, v12, v9
	s_waitcnt lgkmcnt(0)
	v_add_f32_e32 v0, v1, v0
	v_add_f32_e32 v1, v3, v2
	ds_bpermute_b32 v2, v214, v0
	ds_bpermute_b32 v3, v214, v1
	v_cndmask_b32_e32 v4, v8, v12, vcc
	v_lshlrev_b32_e32 v215, 2, v4
	v_cmp_lt_i32_e32 vcc, v13, v9
	s_waitcnt lgkmcnt(1)
	v_add_f32_e32 v0, v0, v2
	s_waitcnt lgkmcnt(0)
	v_add_f32_e32 v1, v1, v3
	ds_bpermute_b32 v2, v215, v0
	ds_bpermute_b32 v3, v215, v1
	v_cndmask_b32_e32 v4, v8, v13, vcc
	v_lshlrev_b32_e32 v216, 2, v4
	v_cmp_lt_i32_e32 vcc, v14, v9
	s_waitcnt lgkmcnt(1)
	v_add_f32_e32 v0, v0, v2
	s_waitcnt lgkmcnt(0)
	v_add_f32_e32 v1, v1, v3
	ds_bpermute_b32 v2, v216, v0
	ds_bpermute_b32 v3, v216, v1
	v_cndmask_b32_e32 v4, v8, v14, vcc
	v_lshlrev_b32_e32 v217, 2, v4
	v_cmp_lt_i32_e32 vcc, v15, v9
	s_waitcnt lgkmcnt(1)
	v_add_f32_e32 v0, v0, v2
	s_waitcnt lgkmcnt(0)
	v_add_f32_e32 v1, v1, v3
	ds_bpermute_b32 v2, v217, v0
	ds_bpermute_b32 v3, v217, v1
	v_cndmask_b32_e32 v4, v8, v15, vcc
	v_lshlrev_b32_e32 v218, 2, v4
	s_waitcnt lgkmcnt(1)
	v_add_f32_e32 v2, v0, v2
	s_waitcnt lgkmcnt(0)
	v_add_f32_e32 v0, v1, v3
	ds_bpermute_b32 v3, v218, v2
	ds_bpermute_b32 v1, v218, v0
	s_cbranch_scc1 .LBB0_302
	s_waitcnt lgkmcnt(1)
	v_add_f32_e32 v2, v2, v3
	s_mov_b32 s0, 0x3fb8aa3b
	v_mul_f32_e32 v3, 0x3fb8aa3b, v2
	v_fma_f32 v4, v2, s0, -v3
	v_rndne_f32_e32 v5, v3
	v_fmac_f32_e32 v4, 0x32a5705f, v2
	v_sub_f32_e32 v3, v3, v5
	v_add_f32_e32 v3, v3, v4
	v_exp_f32_e32 v3, v3
	v_cvt_i32_f32_e32 v4, v5
	s_waitcnt lgkmcnt(0)
	v_add_f32_e32 v0, v0, v1
	s_mov_b32 s1, 0xc2ce8ed0
	v_cmp_ngt_f32_e32 vcc, s1, v2
	v_ldexp_f32 v1, v3, v4
	v_mul_f32_e32 v3, 0x3fb8aa3b, v0
	v_fma_f32 v4, v0, s0, -v3
	v_rndne_f32_e32 v5, v3
	v_fmac_f32_e32 v4, 0x32a5705f, v0
	v_sub_f32_e32 v3, v3, v5
	v_add_f32_e32 v3, v3, v4
	v_exp_f32_e32 v3, v3
	v_cvt_i32_f32_e32 v4, v5
	s_mov_b32 s2, 0x42b17218
	v_cndmask_b32_e32 v1, 0, v1, vcc
	v_mov_b32_e32 v5, 0x7f800000
	v_cmp_nlt_f32_e32 vcc, s2, v2
	v_ldexp_f32 v2, v3, v4
	v_bfe_u32 v222, v212, 5, 1
	v_cndmask_b32_e32 v1, v5, v1, vcc
	v_cmp_ngt_f32_e32 vcc, s1, v0
	v_bfe_u32 v3, v212, 2, 2
	v_lshlrev_b32_e32 v223, 2, v222
	v_cndmask_b32_e32 v2, 0, v2, vcc
	v_cmp_nlt_f32_e32 vcc, s2, v0
	v_lshrrev_b32_e32 v6, 3, v212
	v_and_b32_e32 v221, 31, v212
	v_cndmask_b32_e32 v0, v5, v2, vcc
	v_or_b32_e32 v5, v223, v3
	v_lshlrev_b32_e32 v3, 2, v3
	v_and_b32_e32 v6, 2, v6
	v_bfe_u32 v7, v212, 1, 1
	v_sub_f32_e32 v0, v1, v0
	s_add_u32 s17, s80, 0x12200000
	v_or3_b32 v3, v3, v6, v7
	v_lshlrev_b32_e32 v6, 3, v212
	v_lshlrev_b32_e32 v5, 9, v5
	v_lshlrev_b32_e32 v194, 2, v221
	v_readlane_b32 s0, v255, 27
	v_add_f32_e32 v219, 0x3e4ccccd, v0
	s_addc_u32 s20, s81, 0
	v_lshlrev_b32_e32 v0, 3, v221
	v_mov_b32_e32 v1, 0
	v_and_b32_e32 v6, 8, v6
	v_lshl_or_b32 v3, v3, 4, v5
	v_add_u32_e32 v226, s0, v194
	v_lshl_add_u32 v227, v222, 4, s0
	s_movk_i32 s0, 0x80
	v_readlane_b32 s52, v255, 7
	s_add_u32 s21, s80, 0x16200000
	v_bitop3_b32 v0, v0, v212, 32 bitop3:0x78
	v_lshlrev_b32_e32 v2, 7, v221
	v_lshlrev_b32_e32 v4, 3, v222
	v_lshlrev_b32_e32 v5, 9, v222
	v_lshlrev_b32_e32 v7, 4, v221
	v_bitop3_b32 v229, v3, s0, v6 bitop3:0x36
	s_movk_i32 s0, 0xc0
	v_mov_b32_e32 v195, v1
	v_readlane_b32 s66, v255, 21
	v_readlane_b32 s67, v255, 22
	s_addc_u32 s22, s81, 0
	v_and_b32_e32 v220, 63, v212
	v_or_b32_e32 v224, v3, v6
	v_add3_u32 v225, 0, v5, v7
	v_bitop3_b32 v228, v3, 64, v6 bitop3:0x36
	v_bitop3_b32 v230, v3, s0, v6 bitop3:0x36
	v_lshl_add_u64 v[196:197], s[66:67], 0, v[194:195]
	v_or_b32_e32 v231, 9, v223
	v_or_b32_e32 v232, 10, v223
	v_or_b32_e32 v233, 11, v223
	v_or_b32_e32 v234, 16, v223
	v_or_b32_e32 v235, 17, v223
	v_or_b32_e32 v236, 18, v223
	v_or_b32_e32 v237, 19, v223
	v_or_b32_e32 v238, 24, v223
	v_or_b32_e32 v239, 25, v223
	v_or_b32_e32 v240, 26, v223
	v_or_b32_e32 v241, 27, v223
	v_or_b32_e32 v242, 0x42, v222
	v_or_b32_e32 v243, 64, v222
	s_mov_b64 s[6:7], 0x200000
	v_lshlrev_b32_e32 v198, 1, v0
	s_mov_b64 s[8:9], 0x2000
	s_mov_b64 s[10:11], 0x202000
	v_lshlrev_b32_e32 v200, 1, v2
	v_lshlrev_b32_e32 v202, 1, v4
	s_mov_b64 s[12:13], 0x4000
	s_mov_b64 s[14:15], 0x204000
	s_add_i32 s23, 0, 0x10000
	s_mov_b32 s24, 0xf149f2ca
	s_mov_b64 s[18:19], 0x6000
	v_mov_b32_e32 v244, 0x358637bd
	s_mov_b32 s25, 0xf800000
	v_mov_b32_e32 v245, 0x260
	s_mov_b32 s26, 0x3f4ccccd
	s_mov_b32 s27, 0xa200000
	s_mov_b32 s28, 0x1a202000
	s_mov_b32 s29, 0xa202000
	s_mov_b32 s30, 0x1a204000
	s_mov_b32 s31, 0xa204000
	s_mov_b32 s34, 0x1a206000
	s_mov_b32 s35, 0xa206000
	v_mov_b32_e32 v246, 0xf149f2ca
	s_mov_b32 s36, s84
	v_readlane_b32 s53, v255, 8
	v_readlane_b32 s54, v255, 9
	v_readlane_b32 s55, v255, 10
	v_readlane_b32 s56, v255, 11
	v_readlane_b32 s57, v255, 12
	v_readlane_b32 s58, v255, 13
	v_readlane_b32 s59, v255, 14
	v_readlane_b32 s60, v255, 15
	v_readlane_b32 s61, v255, 16
	v_readlane_b32 s62, v255, 17
	v_readlane_b32 s63, v255, 18
	v_readlane_b32 s64, v255, 19
	v_readlane_b32 s65, v255, 20
	s_branch .LBB0_267

.LBB0_275:
	v_readfirstlane_b32 s39, v212
	s_bfe_u32 s0, s36, 0x40004
	s_lshr_b32 s46, s39, 6
	s_bfe_u32 s38, s39, 0x20006
	s_lshr_b32 s40, s39, 8
	s_lshl_b32 s3, s0, 1
	s_lshl_b32 s4, s0, 22
	s_add_u32 s0, s17, s4
	s_addc_u32 s1, s20, 0
	s_add_u32 s44, s21, s4
	s_addc_u32 s45, s22, 0
	s_lshl_b32 s33, s2, 7
	s_lshl_b32 s37, s38, 5
	s_add_i32 s4, s40, s3
	s_or_b32 s47, s37, s33
	s_lshl_b64 s[42:43], s[4:5], 21
	s_add_u32 s3, s96, s42
	s_addc_u32 s4, s88, s43
	s_lshl_b32 s41, s47, 8
	s_add_u32 s42, s3, s41
	s_addc_u32 s43, s4, 0
	s_and_b32 s3, s39, 0xffffffc0
	s_lshl_b32 s41, s46, 10
	v_or_b32_e32 v0, s3, v220
	s_lshl_b32 s3, s46, 2
	s_add_i32 s4, s41, 0
	v_lshl_add_u64 v[34:35], v[0:1], 4, s[0:1]
	s_mov_b32 s0, m0
	s_mov_b32 m0, s4
	s_nop 0
	global_load_lds_dwordx4 v[34:35], off
	s_mov_b32 m0, s0
	v_or_b32_e32 v0, s3, v222
	s_add_i32 s0, s4, 0x2000
	v_lshlrev_b64 v[2:3], 9, v[0:1]
	v_lshl_add_u64 v[36:37], v[34:35], 0, s[6:7]
	s_mov_b32 s1, m0
	s_mov_b32 m0, s0
	s_nop 0
	global_load_lds_dwordx4 v[36:37], off
	s_mov_b32 m0, s1
	s_lshr_b32 s0, s39, 5
	v_lshl_add_u64 v[2:3], s[44:45], 0, v[2:3]
	v_mov_b32_e32 v199, v1
	v_lshl_add_u64 v[2:3], v[2:3], 0, v[198:199]
	s_add_i32 s1, s4, s41
	s_or_b32 s0, s0, 1
	s_add_i32 s1, s1, 0xc000
	s_mov_b32 s41, m0
	s_mov_b32 m0, s1
	s_nop 0
	global_load_lds_dwordx4 v[2:3], off
	s_mov_b32 m0, s41
	v_lshl_or_b32 v2, s0, 1, v222
	v_mov_b32_e32 v3, v1
	v_lshlrev_b64 v[4:5], 9, v[2:3]
	v_lshlrev_b32_e32 v3, 2, v2
	v_bitop3_b32 v3, v3, v221, 12 bitop3:0x6c
	v_lshl_add_u64 v[4:5], s[44:45], 0, v[4:5]
	v_lshlrev_b32_e32 v6, 4, v3
	v_mov_b32_e32 v7, v1
	s_lshl_b32 s41, s0, 10
	v_lshl_add_u64 v[4:5], v[4:5], 0, v[6:7]
	s_add_i32 s0, s41, 0
	s_add_i32 s0, s0, 0xc000
	s_mov_b32 s1, m0
	s_mov_b32 m0, s0
	s_nop 0
	global_load_lds_dwordx4 v[4:5], off
	s_mov_b32 m0, s1
	v_lshl_add_u64 v[4:5], v[34:35], 0, s[8:9]
	s_add_i32 s0, s4, 0x4000
	s_mov_b32 s1, m0
	s_mov_b32 m0, s0
	s_nop 0
	global_load_lds_dwordx4 v[4:5], off
	s_mov_b32 m0, s1
	v_lshl_add_u64 v[4:5], v[34:35], 0, s[10:11]
	v_mov_b32_e32 v201, v1
	s_addk_i32 s0, 0x2000
	s_mov_b32 s1, m0
	s_mov_b32 m0, s0
	s_nop 0
	global_load_lds_dwordx4 v[4:5], off
	s_mov_b32 m0, s1
	v_lshl_add_u64 v[4:5], s[42:43], 0, v[200:201]
	v_mov_b32_e32 v203, v1
	v_lshl_add_u64 v[4:5], v[4:5], 0, v[202:203]
	global_load_dwordx4 v[146:149], v[4:5], off
	global_load_dwordx4 v[150:153], v[4:5], off offset:32
	global_load_dwordx4 v[154:157], v[4:5], off offset:64
	global_load_dwordx4 v[158:161], v[4:5], off offset:96
	global_load_dwordx4 v[162:165], v[4:5], off offset:128
	global_load_dwordx4 v[166:169], v[4:5], off offset:160
	global_load_dwordx4 v[170:173], v[4:5], off offset:192
	global_load_dwordx4 v[174:177], v[4:5], off offset:224
	s_waitcnt vmcnt(4)
	s_barrier
	v_lshl_add_u64 v[4:5], v[34:35], 0, s[12:13]
	s_add_i32 s0, s4, 0x8000
	s_mov_b32 s1, m0
	s_mov_b32 m0, s0
	s_nop 0
	global_load_lds_dwordx4 v[4:5], off
	s_mov_b32 m0, s1
	v_lshl_add_u64 v[4:5], v[34:35], 0, s[14:15]
	v_add_u32_e32 v0, 32, v0
	s_lshl_b32 s42, s46, 11
	v_lshl_add_u64 v[38:39], s[44:45], 0, v[198:199]
	s_addk_i32 s0, 0x2000
	s_mov_b32 s1, m0
	s_mov_b32 m0, s0
	s_nop 0
	global_load_lds_dwordx4 v[4:5], off
	s_mov_b32 m0, s1
	v_lshlrev_b64 v[4:5], 9, v[0:1]
	v_add_u32_e32 v0, 32, v2
	v_lshl_add_u64 v[40:41], s[44:45], 0, v[6:7]
	v_lshl_add_u64 v[4:5], v[38:39], 0, v[4:5]
	s_add_i32 s0, s23, s42
	s_mov_b32 s1, m0
	s_mov_b32 m0, s0
	s_nop 0
	global_load_lds_dwordx4 v[4:5], off
	s_mov_b32 m0, s1
	v_lshlrev_b64 v[2:3], 9, v[0:1]
	v_lshl_add_u32 v199, s40, 13, v225
	v_lshl_add_u64 v[2:3], v[40:41], 0, v[2:3]
	s_add_i32 s0, s23, s41
	s_mov_b32 s1, m0
	s_mov_b32 m0, s0
	s_nop 0
	global_load_lds_dwordx4 v[2:3], off
	s_mov_b32 m0, s1
	ds_read_b128 v[2:5], v199
	v_or_b32_e32 v201, s47, v221
	ds_read_b128 v[6:9], v199 offset:1024
	s_waitcnt vmcnt(7) lgkmcnt(1)
	v_mfma_f32_32x32x16_bf16 v[18:33], v[2:5], v[146:149], 0
	ds_read_b128 v[2:5], v199 offset:2048
	s_waitcnt vmcnt(6) lgkmcnt(1)
	v_mfma_f32_32x32x16_bf16 v[18:33], v[6:9], v[150:153], v[18:33]
	ds_read_b128 v[6:9], v199 offset:3072
	s_waitcnt vmcnt(5) lgkmcnt(1)
	v_mfma_f32_32x32x16_bf16 v[18:33], v[2:5], v[154:157], v[18:33]
	ds_read_b128 v[2:5], v199 offset:4096
	s_waitcnt vmcnt(4) lgkmcnt(1)
	v_mfma_f32_32x32x16_bf16 v[18:33], v[6:9], v[158:161], v[18:33]
	ds_read_b128 v[6:9], v199 offset:5120
	s_waitcnt vmcnt(3) lgkmcnt(1)
	v_mfma_f32_32x32x16_bf16 v[18:33], v[2:5], v[162:165], v[18:33]
	ds_read_b128 v[2:5], v199 offset:6144
	s_waitcnt vmcnt(2) lgkmcnt(1)
	v_mfma_f32_32x32x16_bf16 v[18:33], v[6:9], v[166:169], v[18:33]
	ds_read_b128 v[6:9], v199 offset:7168
	s_waitcnt vmcnt(1) lgkmcnt(1)
	v_mfma_f32_32x32x16_bf16 v[18:33], v[2:5], v[170:173], v[18:33]
	s_waitcnt vmcnt(0) lgkmcnt(0)
	v_mfma_f32_32x32x16_bf16 v[18:33], v[6:9], v[174:177], v[18:33]
	s_cmp_lg_u32 s2, 0
	s_cbranch_scc1 .LBB0_277
	v_cmp_lt_u32_e32 vcc, v223, v201
	v_or_b32_e32 v0, 2, v223
	s_nop 6
	v_cndmask_b32_e32 v19, v246, v19, vcc
	v_cmp_le_u32_e32 vcc, v223, v201
	s_nop 1
	v_cndmask_b32_e32 v18, v246, v18, vcc
	v_cmp_le_u32_e32 vcc, v0, v201
	v_or_b32_e32 v0, 3, v223
	s_nop 0
	v_cndmask_b32_e32 v20, v246, v20, vcc
	v_cmp_le_u32_e32 vcc, v0, v201
	v_or_b32_e32 v0, 8, v223
	s_nop 0
	v_cndmask_b32_e32 v21, v246, v21, vcc
	v_cmp_le_u32_e32 vcc, v0, v201
	s_nop 1
	v_cndmask_b32_e32 v22, v246, v22, vcc
	v_cmp_le_u32_e32 vcc, v231, v201
	s_nop 1
	v_cndmask_b32_e32 v23, v246, v23, vcc
	v_cmp_le_u32_e32 vcc, v232, v201
	s_nop 1
	v_cndmask_b32_e32 v24, v246, v24, vcc
	v_cmp_le_u32_e32 vcc, v233, v201
	s_nop 1
	v_cndmask_b32_e32 v25, v246, v25, vcc
	v_cmp_le_u32_e32 vcc, v234, v201
	s_nop 1
	v_cndmask_b32_e32 v26, v246, v26, vcc
	v_cmp_le_u32_e32 vcc, v235, v201
	s_nop 1
	v_cndmask_b32_e32 v27, v246, v27, vcc
	v_cmp_le_u32_e32 vcc, v236, v201
	s_nop 1
	v_cndmask_b32_e32 v28, v246, v28, vcc
	v_cmp_le_u32_e32 vcc, v237, v201
	s_nop 1
	v_cndmask_b32_e32 v29, v246, v29, vcc
	v_cmp_le_u32_e32 vcc, v238, v201
	s_nop 1
	v_cndmask_b32_e32 v30, v246, v30, vcc
	v_cmp_le_u32_e32 vcc, v239, v201
	s_nop 1
	v_cndmask_b32_e32 v31, v246, v31, vcc
	v_cmp_le_u32_e32 vcc, v240, v201
	s_nop 1
	v_cndmask_b32_e32 v32, v246, v32, vcc
	v_cmp_le_u32_e32 vcc, v241, v201
	s_nop 1
	v_cndmask_b32_e32 v33, v246, v33, vcc

.LBB0_356:
	s_setprio 0
	s_cmp_lt_i32 s62, 4
	s_cselect_b64 s[0:1], -1, 0
	s_cmp_gt_i32 s63, 3
	s_cselect_b64 s[2:3], -1, 0
	s_and_b64 s[0:1], s[0:1], s[2:3]
	s_andn2_b64 vcc, exec, s[0:1]
	s_cbranch_vccnz .LBB0_435
	v_mov_b32_e32 v0, v212
	s_waitcnt vmcnt(0)
	s_cmpk_gt_i32 s93, 0x1ff
	v_readfirstlane_b32 s3, v212
	s_cbranch_scc1 .LBB0_381
	s_ashr_i32 s17, s93, 31
	s_lshr_b32 s0, s17, 29
	s_add_i32 s4, s93, s0
	s_and_b32 s0, s4, -8
	s_sub_i32 s5, s93, s0
	s_cmp_gt_i32 s5, -1
	s_cbranch_scc0 .LBB0_360
	s_lshl_b32 s2, s5, 6
	s_cbranch_execz .LBB0_361
	s_branch .LBB0_362

.LBB0_1587:
	s_cmp_lt_i32 s62, 18
	s_cselect_b64 s[0:1], -1, 0
	s_cmp_gt_i32 s63, 17
	s_cselect_b64 s[2:3], -1, 0
	s_and_b64 s[0:1], s[0:1], s[2:3]
	s_andn2_b64 vcc, exec, s[0:1]
	s_cbranch_vccnz .LBB0_1680
	v_readfirstlane_b32 s0, v212
	s_cmp_lt_u32 s0, 0x100
	s_cbranch_scc1 .Lmy_prio_b
	s_setprio 1
.Lmy_prio_b:
	v_mov_b32_e32 v0, v212
	v_readlane_b32 s0, v255, 7
	v_and_b32_e32 v0, 63, v0
	v_lshlrev_b32_e32 v0, 2, v0
	v_readlane_b32 s12, v255, 19
	v_readlane_b32 s13, v255, 20
	s_nop 4
	global_load_dword v1, v0, s[12:13] offset:2816
	global_load_dword v2, v0, s[12:13] offset:3072
	global_load_dword v3, v0, s[12:13] offset:3840
	global_load_dword v4, v0, s[12:13] offset:3328
	global_load_dword v5, v0, s[12:13] offset:2304
	global_load_dword v6, v0, s[12:13] offset:2560
	global_load_dword v7, v0, s[12:13] offset:2048
	global_load_dword v8, v0, s[12:13] offset:3584
	v_mbcnt_lo_u32_b32 v0, -1, 0
	v_mbcnt_hi_u32_b32 v0, -1, v0
	v_and_b32_e32 v9, 64, v0
	v_xor_b32_e32 v10, 1, v0
	v_add_u32_e32 v9, 64, v9
	v_cmp_lt_i32_e32 vcc, v10, v9
	v_xor_b32_e32 v11, 2, v0
	v_xor_b32_e32 v12, 4, v0
	v_cndmask_b32_e32 v10, v0, v10, vcc
	v_lshlrev_b32_e32 v213, 2, v10
	v_cmp_lt_i32_e32 vcc, v11, v9
	v_xor_b32_e32 v13, 8, v0
	v_xor_b32_e32 v14, 16, v0
	v_xor_b32_e32 v15, 32, v0
	v_readlane_b32 s5, v255, 12
	s_cmpk_gt_i32 s84, 0x3ff
	s_mov_b32 s5, 0
	v_readlane_b32 s1, v255, 8
	v_readlane_b32 s2, v255, 9
	v_readlane_b32 s3, v255, 10
	v_readlane_b32 s4, v255, 11
	v_readlane_b32 s6, v255, 13
	v_readlane_b32 s7, v255, 14
	v_readlane_b32 s8, v255, 15
	v_readlane_b32 s9, v255, 16
	v_readlane_b32 s10, v255, 17
	v_readlane_b32 s11, v255, 18
	v_readlane_b32 s14, v255, 21
	v_readlane_b32 s15, v255, 22
	s_waitcnt vmcnt(0)
	v_mul_f32_e32 v3, v4, v3
	v_mul_f32_e32 v1, v5, v1
	v_cndmask_b32_e32 v5, v0, v11, vcc
	v_fmac_f32_e32 v1, v7, v6
	v_fmac_f32_e32 v3, v2, v8
	ds_bpermute_b32 v2, v213, v1
	ds_bpermute_b32 v4, v213, v3
	v_lshlrev_b32_e32 v214, 2, v5
	v_cmp_lt_i32_e32 vcc, v12, v9
	s_waitcnt lgkmcnt(0)
	v_add_f32_e32 v1, v1, v2
	v_add_f32_e32 v2, v3, v4
	ds_bpermute_b32 v3, v214, v1
	ds_bpermute_b32 v4, v214, v2
	v_cndmask_b32_e32 v5, v0, v12, vcc
	v_lshlrev_b32_e32 v215, 2, v5
	v_cmp_lt_i32_e32 vcc, v13, v9
	s_waitcnt lgkmcnt(1)
	v_add_f32_e32 v1, v1, v3
	s_waitcnt lgkmcnt(0)
	v_add_f32_e32 v2, v2, v4
	ds_bpermute_b32 v3, v215, v1
	ds_bpermute_b32 v4, v215, v2
	v_cndmask_b32_e32 v5, v0, v13, vcc
	v_lshlrev_b32_e32 v216, 2, v5
	v_cmp_lt_i32_e32 vcc, v14, v9
	s_waitcnt lgkmcnt(1)
	v_add_f32_e32 v1, v1, v3
	s_waitcnt lgkmcnt(0)
	v_add_f32_e32 v2, v2, v4
	ds_bpermute_b32 v3, v216, v1
	ds_bpermute_b32 v4, v216, v2
	v_cndmask_b32_e32 v5, v0, v14, vcc
	v_lshlrev_b32_e32 v217, 2, v5
	v_cmp_lt_i32_e32 vcc, v15, v9
	s_waitcnt lgkmcnt(1)
	v_add_f32_e32 v1, v1, v3
	s_waitcnt lgkmcnt(0)
	v_add_f32_e32 v3, v2, v4
	ds_bpermute_b32 v2, v217, v1
	ds_bpermute_b32 v4, v217, v3
	v_cndmask_b32_e32 v0, v0, v15, vcc
	v_lshlrev_b32_e32 v218, 2, v0
	s_waitcnt lgkmcnt(1)
	v_add_f32_e32 v2, v1, v2
	s_waitcnt lgkmcnt(0)
	v_add_f32_e32 v0, v3, v4
	ds_bpermute_b32 v3, v218, v2
	ds_bpermute_b32 v1, v218, v0
	s_cbranch_scc1 .LBB0_1626
	s_waitcnt lgkmcnt(1)
	v_add_f32_e32 v2, v2, v3
	s_mov_b32 s0, 0x3fb8aa3b
	v_mul_f32_e32 v3, 0x3fb8aa3b, v2
	v_fma_f32 v4, v2, s0, -v3
	v_rndne_f32_e32 v5, v3
	v_fmac_f32_e32 v4, 0x32a5705f, v2
	v_sub_f32_e32 v3, v3, v5
	v_add_f32_e32 v3, v3, v4
	v_exp_f32_e32 v3, v3
	v_cvt_i32_f32_e32 v4, v5
	s_waitcnt lgkmcnt(0)
	v_add_f32_e32 v0, v0, v1
	s_mov_b32 s1, 0xc2ce8ed0
	v_cmp_ngt_f32_e32 vcc, s1, v2
	v_ldexp_f32 v1, v3, v4
	v_mul_f32_e32 v3, 0x3fb8aa3b, v0
	v_fma_f32 v4, v0, s0, -v3
	v_rndne_f32_e32 v5, v3
	v_fmac_f32_e32 v4, 0x32a5705f, v0
	v_sub_f32_e32 v3, v3, v5
	v_add_f32_e32 v3, v3, v4
	v_exp_f32_e32 v3, v3
	v_cvt_i32_f32_e32 v4, v5
	s_mov_b32 s2, 0x42b17218
	v_cndmask_b32_e32 v1, 0, v1, vcc
	v_mov_b32_e32 v5, 0x7f800000
	v_cmp_nlt_f32_e32 vcc, s2, v2
	v_ldexp_f32 v2, v3, v4
	v_bfe_u32 v222, v212, 5, 1
	v_cndmask_b32_e32 v1, v5, v1, vcc
	v_cmp_ngt_f32_e32 vcc, s1, v0
	v_bfe_u32 v3, v212, 2, 2
	v_lshlrev_b32_e32 v223, 2, v222
	v_cndmask_b32_e32 v2, 0, v2, vcc
	v_cmp_nlt_f32_e32 vcc, s2, v0
	v_lshrrev_b32_e32 v6, 3, v212
	v_and_b32_e32 v221, 31, v212
	v_cndmask_b32_e32 v0, v5, v2, vcc
	v_or_b32_e32 v5, v223, v3
	v_lshlrev_b32_e32 v3, 2, v3
	v_and_b32_e32 v6, 2, v6
	v_bfe_u32 v7, v212, 1, 1
	s_add_u32 s18, s80, 0x12200000
	v_or3_b32 v3, v3, v6, v7
	v_lshlrev_b32_e32 v6, 3, v212
	v_lshlrev_b32_e32 v5, 9, v5
	v_lshlrev_b32_e32 v194, 2, v221
	v_readlane_b32 s0, v255, 27
	s_addc_u32 s19, s81, 0
	v_and_b32_e32 v6, 8, v6
	v_lshl_or_b32 v3, v3, 4, v5
	v_add_u32_e32 v226, s0, v194
	v_lshl_add_u32 v227, v222, 4, s0
	s_movk_i32 s0, 0x80
	v_sub_f32_e32 v0, v1, v0
	s_add_u32 s20, s80, 0x16200000
	v_bitop3_b32 v229, v3, s0, v6 bitop3:0x36
	s_movk_i32 s0, 0xc0
	v_add_f32_e32 v219, 0x3f0e59d5, v0
	s_addc_u32 s21, s81, 0
	v_lshlrev_b32_e32 v0, 3, v221
	v_mov_b32_e32 v1, 0
	v_bitop3_b32 v230, v3, s0, v6 bitop3:0x36
	s_mov_b64 s[0:1], s[80:81]
	s_mov_b32 s48, s84
	s_mov_b64 s[2:3], s[86:87]
	s_mov_b32 s49, s88
	s_mov_b32 s4, s82
	v_readlane_b32 s80, v255, 7
	v_bitop3_b32 v0, v0, v212, 32 bitop3:0x78
	v_lshlrev_b32_e32 v2, 7, v221
	v_lshlrev_b32_e32 v4, 3, v222
	v_lshlrev_b32_e32 v5, 9, v222
	v_lshlrev_b32_e32 v7, 4, v221
	v_mov_b32_e32 v195, v1
	v_readlane_b32 s81, v255, 8
	v_readlane_b32 s82, v255, 9
	v_readlane_b32 s86, v255, 13
	v_readlane_b32 s87, v255, 14
	v_readlane_b32 s93, v255, 20
	v_readlane_b32 s94, v255, 21
	v_readlane_b32 s95, v255, 22
	v_and_b32_e32 v220, 63, v212
	v_or_b32_e32 v224, v3, v6
	v_add3_u32 v225, 0, v5, v7
	v_bitop3_b32 v228, v3, 64, v6 bitop3:0x36
	s_mov_b32 s82, s4
	s_mov_b64 s[86:87], s[2:3]
	s_mov_b64 s[80:81], s[0:1]
	s_mov_b32 s93, s97
	v_lshl_add_u64 v[196:197], s[94:95], 0, v[194:195]
	v_or_b32_e32 v231, 9, v223
	v_or_b32_e32 v232, 10, v223
	v_or_b32_e32 v233, 11, v223
	v_or_b32_e32 v234, 16, v223
	v_or_b32_e32 v235, 17, v223
	v_or_b32_e32 v236, 18, v223
	v_or_b32_e32 v237, 19, v223
	v_or_b32_e32 v238, 24, v223
	v_or_b32_e32 v239, 25, v223
	v_or_b32_e32 v240, 26, v223
	v_or_b32_e32 v241, 27, v223
	v_or_b32_e32 v242, 0x42, v222
	v_or_b32_e32 v243, 64, v222
	s_mov_b64 s[6:7], 0x200000
	v_lshlrev_b32_e32 v198, 1, v0
	s_mov_b64 s[8:9], 0x2000
	s_mov_b64 s[10:11], 0x202000
	v_lshlrev_b32_e32 v200, 1, v2
	v_lshlrev_b32_e32 v202, 1, v4
	s_mov_b64 s[12:13], 0x4000
	s_mov_b64 s[14:15], 0x204000
	s_add_i32 s22, 0, 0x10000
	s_mov_b32 s23, 0xf149f2ca
	s_mov_b64 s[16:17], 0x6000
	v_mov_b32_e32 v244, 0x358637bd
	s_mov_b32 s24, 0xf800000
	v_mov_b32_e32 v245, 0x260
	s_mov_b32 s25, 0x3ee34c56
	s_mov_b32 s26, 0xa200000
	s_mov_b32 s27, 0x1a202000
	s_mov_b32 s28, 0xa202000
	s_mov_b32 s29, 0x1a204000
	s_mov_b32 s30, 0xa204000
	s_mov_b32 s31, 0x1a206000
	s_mov_b32 s34, 0xa206000
	v_mov_b32_e32 v246, 0xf149f2ca
	v_readlane_b32 s83, v255, 10
	v_readlane_b32 s84, v255, 11
	v_readlane_b32 s85, v255, 12
	v_readlane_b32 s88, v255, 15
	v_readlane_b32 s89, v255, 16
	v_readlane_b32 s90, v255, 17
	v_readlane_b32 s91, v255, 18
	v_readlane_b32 s92, v255, 19
	s_branch .LBB0_1591

.LBB0_1599:
	v_readfirstlane_b32 s37, v212
	s_bfe_u32 s0, s48, 0x40004
	s_lshr_b32 s44, s37, 6
	s_bfe_u32 s36, s37, 0x20006
	s_lshr_b32 s38, s37, 8
	s_lshl_b32 s3, s0, 1
	s_lshl_b32 s4, s0, 22
	s_add_u32 s0, s18, s4
	s_addc_u32 s1, s19, 0
	s_add_u32 s42, s20, s4
	s_addc_u32 s43, s21, 0
	s_lshl_b32 s33, s2, 7
	s_lshl_b32 s35, s36, 5
	s_add_i32 s4, s38, s3
	s_or_b32 s45, s35, s33
	s_lshl_b64 s[40:41], s[4:5], 21
	s_add_u32 s3, s96, s40
	s_addc_u32 s4, s49, s41
	s_lshl_b32 s39, s45, 8
	s_add_u32 s40, s3, s39
	s_addc_u32 s41, s4, 0
	s_and_b32 s3, s37, 0xffffffc0
	s_lshl_b32 s39, s44, 10
	v_or_b32_e32 v0, s3, v220
	s_lshl_b32 s3, s44, 2
	s_add_i32 s4, s39, 0
	v_lshl_add_u64 v[34:35], v[0:1], 4, s[0:1]
	s_mov_b32 s0, m0
	s_mov_b32 m0, s4
	s_nop 0
	global_load_lds_dwordx4 v[34:35], off
	s_mov_b32 m0, s0
	v_or_b32_e32 v0, s3, v222
	s_add_i32 s0, s4, 0x2000
	v_lshlrev_b64 v[2:3], 9, v[0:1]
	v_lshl_add_u64 v[36:37], v[34:35], 0, s[6:7]
	s_mov_b32 s1, m0
	s_mov_b32 m0, s0
	s_nop 0
	global_load_lds_dwordx4 v[36:37], off
	s_mov_b32 m0, s1
	s_lshr_b32 s0, s37, 5
	v_lshl_add_u64 v[2:3], s[42:43], 0, v[2:3]
	v_mov_b32_e32 v199, v1
	v_lshl_add_u64 v[2:3], v[2:3], 0, v[198:199]
	s_add_i32 s1, s4, s39
	s_or_b32 s0, s0, 1
	s_add_i32 s1, s1, 0xc000
	s_mov_b32 s39, m0
	s_mov_b32 m0, s1
	s_nop 0
	global_load_lds_dwordx4 v[2:3], off
	s_mov_b32 m0, s39
	v_lshl_or_b32 v2, s0, 1, v222
	v_mov_b32_e32 v3, v1
	v_lshlrev_b64 v[4:5], 9, v[2:3]
	v_lshlrev_b32_e32 v3, 2, v2
	v_bitop3_b32 v3, v3, v221, 12 bitop3:0x6c
	v_lshl_add_u64 v[4:5], s[42:43], 0, v[4:5]
	v_lshlrev_b32_e32 v6, 4, v3
	v_mov_b32_e32 v7, v1
	s_lshl_b32 s39, s0, 10
	v_lshl_add_u64 v[4:5], v[4:5], 0, v[6:7]
	s_add_i32 s0, s39, 0
	s_add_i32 s0, s0, 0xc000
	s_mov_b32 s1, m0
	s_mov_b32 m0, s0
	s_nop 0
	global_load_lds_dwordx4 v[4:5], off
	s_mov_b32 m0, s1
	v_lshl_add_u64 v[4:5], v[34:35], 0, s[8:9]
	s_add_i32 s0, s4, 0x4000
	s_mov_b32 s1, m0
	s_mov_b32 m0, s0
	s_nop 0
	global_load_lds_dwordx4 v[4:5], off
	s_mov_b32 m0, s1
	v_lshl_add_u64 v[4:5], v[34:35], 0, s[10:11]
	v_mov_b32_e32 v201, v1
	s_addk_i32 s0, 0x2000
	s_mov_b32 s1, m0
	s_mov_b32 m0, s0
	s_nop 0
	global_load_lds_dwordx4 v[4:5], off
	s_mov_b32 m0, s1
	v_lshl_add_u64 v[4:5], s[40:41], 0, v[200:201]
	v_mov_b32_e32 v203, v1
	v_lshl_add_u64 v[4:5], v[4:5], 0, v[202:203]
	global_load_dwordx4 v[146:149], v[4:5], off
	global_load_dwordx4 v[150:153], v[4:5], off offset:32
	global_load_dwordx4 v[154:157], v[4:5], off offset:64
	global_load_dwordx4 v[158:161], v[4:5], off offset:96
	global_load_dwordx4 v[162:165], v[4:5], off offset:128
	global_load_dwordx4 v[166:169], v[4:5], off offset:160
	global_load_dwordx4 v[170:173], v[4:5], off offset:192
	global_load_dwordx4 v[174:177], v[4:5], off offset:224
	s_waitcnt vmcnt(4)
	s_barrier
	v_lshl_add_u64 v[4:5], v[34:35], 0, s[12:13]
	s_add_i32 s0, s4, 0x8000
	s_mov_b32 s1, m0
	s_mov_b32 m0, s0
	s_nop 0
	global_load_lds_dwordx4 v[4:5], off
	s_mov_b32 m0, s1
	v_lshl_add_u64 v[4:5], v[34:35], 0, s[14:15]
	v_add_u32_e32 v0, 32, v0
	s_lshl_b32 s40, s44, 11
	v_lshl_add_u64 v[38:39], s[42:43], 0, v[198:199]
	s_addk_i32 s0, 0x2000
	s_mov_b32 s1, m0
	s_mov_b32 m0, s0
	s_nop 0
	global_load_lds_dwordx4 v[4:5], off
	s_mov_b32 m0, s1
	v_lshlrev_b64 v[4:5], 9, v[0:1]
	v_add_u32_e32 v0, 32, v2
	v_lshl_add_u64 v[40:41], s[42:43], 0, v[6:7]
	v_lshl_add_u64 v[4:5], v[38:39], 0, v[4:5]
	s_add_i32 s0, s22, s40
	s_mov_b32 s1, m0
	s_mov_b32 m0, s0
	s_nop 0
	global_load_lds_dwordx4 v[4:5], off
	s_mov_b32 m0, s1
	v_lshlrev_b64 v[2:3], 9, v[0:1]
	v_lshl_add_u32 v199, s38, 13, v225
	v_lshl_add_u64 v[2:3], v[40:41], 0, v[2:3]
	s_add_i32 s0, s22, s39
	s_mov_b32 s1, m0
	s_mov_b32 m0, s0
	s_nop 0
	global_load_lds_dwordx4 v[2:3], off
	s_mov_b32 m0, s1
	ds_read_b128 v[2:5], v199
	v_or_b32_e32 v201, s45, v221
	ds_read_b128 v[6:9], v199 offset:1024
	s_waitcnt vmcnt(7) lgkmcnt(1)
	v_mfma_f32_32x32x16_bf16 v[18:33], v[2:5], v[146:149], 0
	ds_read_b128 v[2:5], v199 offset:2048
	s_waitcnt vmcnt(6) lgkmcnt(1)
	v_mfma_f32_32x32x16_bf16 v[18:33], v[6:9], v[150:153], v[18:33]
	ds_read_b128 v[6:9], v199 offset:3072
	s_waitcnt vmcnt(5) lgkmcnt(1)
	v_mfma_f32_32x32x16_bf16 v[18:33], v[2:5], v[154:157], v[18:33]
	ds_read_b128 v[2:5], v199 offset:4096
	s_waitcnt vmcnt(4) lgkmcnt(1)
	v_mfma_f32_32x32x16_bf16 v[18:33], v[6:9], v[158:161], v[18:33]
	ds_read_b128 v[6:9], v199 offset:5120
	s_waitcnt vmcnt(3) lgkmcnt(1)
	v_mfma_f32_32x32x16_bf16 v[18:33], v[2:5], v[162:165], v[18:33]
	ds_read_b128 v[2:5], v199 offset:6144
	s_waitcnt vmcnt(2) lgkmcnt(1)
	v_mfma_f32_32x32x16_bf16 v[18:33], v[6:9], v[166:169], v[18:33]
	ds_read_b128 v[6:9], v199 offset:7168
	s_waitcnt vmcnt(1) lgkmcnt(1)
	v_mfma_f32_32x32x16_bf16 v[18:33], v[2:5], v[170:173], v[18:33]
	s_waitcnt vmcnt(0) lgkmcnt(0)
	v_mfma_f32_32x32x16_bf16 v[18:33], v[6:9], v[174:177], v[18:33]
	s_cmp_lg_u32 s2, 0
	s_cbranch_scc1 .LBB0_1601
	v_cmp_lt_u32_e32 vcc, v223, v201
	v_or_b32_e32 v0, 2, v223
	s_nop 6
	v_cndmask_b32_e32 v19, v246, v19, vcc
	v_cmp_le_u32_e32 vcc, v223, v201
	s_nop 1
	v_cndmask_b32_e32 v18, v246, v18, vcc
	v_cmp_le_u32_e32 vcc, v0, v201
	v_or_b32_e32 v0, 3, v223
	s_nop 0
	v_cndmask_b32_e32 v20, v246, v20, vcc
	v_cmp_le_u32_e32 vcc, v0, v201
	v_or_b32_e32 v0, 8, v223
	s_nop 0
	v_cndmask_b32_e32 v21, v246, v21, vcc
	v_cmp_le_u32_e32 vcc, v0, v201
	s_nop 1
	v_cndmask_b32_e32 v22, v246, v22, vcc
	v_cmp_le_u32_e32 vcc, v231, v201
	s_nop 1
	v_cndmask_b32_e32 v23, v246, v23, vcc
	v_cmp_le_u32_e32 vcc, v232, v201
	s_nop 1
	v_cndmask_b32_e32 v24, v246, v24, vcc
	v_cmp_le_u32_e32 vcc, v233, v201
	s_nop 1
	v_cndmask_b32_e32 v25, v246, v25, vcc
	v_cmp_le_u32_e32 vcc, v234, v201
	s_nop 1
	v_cndmask_b32_e32 v26, v246, v26, vcc
	v_cmp_le_u32_e32 vcc, v235, v201
	s_nop 1
	v_cndmask_b32_e32 v27, v246, v27, vcc
	v_cmp_le_u32_e32 vcc, v236, v201
	s_nop 1
	v_cndmask_b32_e32 v28, v246, v28, vcc
	v_cmp_le_u32_e32 vcc, v237, v201
	s_nop 1
	v_cndmask_b32_e32 v29, v246, v29, vcc
	v_cmp_le_u32_e32 vcc, v238, v201
	s_nop 1
	v_cndmask_b32_e32 v30, v246, v30, vcc
	v_cmp_le_u32_e32 vcc, v239, v201
	s_nop 1
	v_cndmask_b32_e32 v31, v246, v31, vcc
	v_cmp_le_u32_e32 vcc, v240, v201
	s_nop 1
	v_cndmask_b32_e32 v32, v246, v32, vcc
	v_cmp_le_u32_e32 vcc, v241, v201
	s_nop 1
	v_cndmask_b32_e32 v33, v246, v33, vcc

.LBB0_1680:
	s_setprio 0
	s_cmp_lt_i32 s62, 19
	s_cselect_b64 s[0:1], -1, 0
	s_cmp_gt_i32 s63, 18
	s_cselect_b64 s[2:3], -1, 0
	s_and_b64 s[0:1], s[0:1], s[2:3]
	s_andn2_b64 vcc, exec, s[0:1]
	s_cbranch_vccnz .LBB0_1759
	v_mov_b32_e32 v0, v212
	s_waitcnt vmcnt(0)
	s_cmpk_gt_i32 s93, 0x1ff
	v_readfirstlane_b32 s3, v212
	s_cbranch_scc1 .LBB0_1705
	s_ashr_i32 s24, s93, 31
	s_lshr_b32 s0, s24, 29
	s_add_i32 s5, s93, s0
	s_and_b32 s0, s5, -8
	s_sub_i32 s4, s93, s0
	s_cmp_gt_i32 s4, -1
	s_cbranch_scc0 .LBB0_1684
	s_lshl_b32 s2, s4, 6
	s_ashr_i32 s0, s5, 3
	s_cbranch_execz .LBB0_1685
	s_branch .LBB0_1686
